# P5 loop: mid-iteration lgkmcnt(0) (guarding only a zero-fill) replaced by s_nop so the second half of the loads does not wait for the first half
# speedup vs baseline: 1.0028x; 1.0015x over previous
; __global__ void __launch_bounds__(512, 2) fwd_mega(Args args) {
;     ...
;                 for (int u = 0; u < NB; ++u) {
;                     const int task = (it0 + u) * 4 + grp, tok = task >> 3, hd = task & 7;
;                     pos[u] = (float)positions[tok];
;                     qa[u] = (u32x4){0u, 0u, 0u, 0u}; ka[u] = (u32x4){0u, 0u, 0u, 0u}; kb0[u] = (f32x4){0.f, 0.f, 0.f, 0.f}; kb1[u] = (f32x4){0.f, 0.f, 0.f, 0.f};
;                     if (m < 8) ka[u] = *(const u32x4*)(KN + (size_t)tok * 512 + hd * 64 + 8 * m);
;                     if (isrope) { kb0[u] = *(const f32x4*)(KR + (size_t)tok * 32 + 8 * (m - 8)); kb1[u] = *(const f32x4*)(KR + (size_t)tok * 32 + 8 * (m - 8) + 4); }
;                 }
.LBB0_1375:
	s_or_b64 exec, exec, s[12:13]
	v_mov_b32_e32 v12, 0
	s_nop 0
	v_mov_b32_e32 v24, 0
	v_mov_b32_e32 v25, 0
	v_mov_b32_e32 v26, 0
	v_mov_b32_e32 v27, 0
	v_mov_b32_e32 v28, 0
	v_mov_b32_e32 v29, 0
	v_mov_b32_e32 v30, 0
	v_mov_b32_e32 v31, 0
	s_and_saveexec_b64 s[12:13], s[4:5]
	s_cbranch_execz .LBB0_1377
	s_lshl_b64 s[22:23], s[18:19], 7
	v_lshl_add_u64 v[14:15], v[66:67], 0, s[22:23]
	v_add_co_u32_e32 v14, vcc, 0x3cff000, v14
	s_nop 1
	v_addc_co_u32_e32 v15, vcc, 0, v15, vcc
	flat_load_dwordx4 v[24:27], v[14:15] offset:3840
	flat_load_dwordx4 v[28:31], v[14:15] offset:3856
